# gdnfin loop-head tile loads issued together (one wait instead of four)
# speedup vs baseline: 1.0482x; 1.0016x over previous
.LBB0_98:
	s_waitcnt vmcnt(0)
	v_mov_b32_e32 v20, v133
	s_waitcnt lgkmcnt(0)
	s_barrier
	s_load_dwordx2 s[6:7], s[0:1], 0x130
	v_ashrrev_i32_e32 v10, 2, v20
	v_ashrrev_i32_e32 v11, 31, v10
	v_lshlrev_b64 v[12:13], 7, v[10:11]
	v_and_b32_e32 v0, 3, v20
	v_lshl_or_b32 v2, v0, 5, v12
	v_mov_b32_e32 v3, v13
	s_waitcnt lgkmcnt(0)
	v_lshl_add_u64 v[2:3], s[6:7], 0, v[2:3]
	v_lshl_add_u64 v[6:7], v[2:3], 0, s[8:9]
	global_load_dwordx4 v[2:5], v[6:7], off
	s_nop 0
	global_load_dwordx4 v[6:9], v[6:7], off offset:-16
	v_lshlrev_b32_e32 v0, 5, v20
	v_mul_lo_u32 v14, v10, s17
	v_and_b32_e32 v0, 0x60, v0
	v_add3_u32 v10, 0, v14, v0
	s_mov_b64 s[10:11], 0xec27800
	s_ashr_i32 s5, s4, 31
	s_movk_i32 s3, 0x7f
	v_and_b32_e32 v18, 63, v20
	v_cmp_lt_i32_e32 vcc, s3, v20
	v_lshl_add_u64 v[150:151], s[6:7], 0, v[12:13]
	v_lshl_add_u64 v[150:151], v[150:151], 0, v[0:1]
	v_lshl_add_u64 v[152:153], v[150:151], 0, s[10:11]
	s_lshl_b64 s[10:11], s[4:5], 13
	v_lshl_add_u64 v[154:155], v[152:153], 0, s[10:11]
	global_load_dwordx4 v[134:137], v[154:155], off offset:16
	global_load_dwordx4 v[138:141], v[154:155], off
	s_add_i32 s10, s4, 1
	s_ashr_i32 s11, s10, 31
	s_lshl_b64 s[12:13], s[10:11], 13
	v_lshl_add_u64 v[154:155], v[152:153], 0, s[12:13]
	global_load_dwordx4 v[142:145], v[154:155], off offset:16
	global_load_dwordx4 v[146:149], v[154:155], off
	v_ashrrev_i32_e32 v19, 6, v20
	s_mov_b64 s[12:13], exec
	s_andn2_b64 exec, exec, vcc
	v_add_u32_e32 v156, s4, v19
	v_lshlrev_b32_e32 v156, 10, v156
	v_lshl_add_u32 v156, v18, 2, v156
	v_add_u32_e32 v156, 0x327800, v156
	v_mov_b32_e32 v157, 0
	v_lshl_add_u64 v[156:157], s[6:7], 0, v[156:157]
	global_load_dword v160, v[156:157], off
	s_mov_b64 exec, s[12:13]
	s_waitcnt vmcnt(0)
	ds_write_b128 v10, v[6:9]
	ds_write_b128 v10, v[2:5] offset:16
	v_add3_u32 v0, 0, v0, v14
	ds_write_b128 v0, v[138:141] offset:9216
	ds_write_b128 v0, v[134:137] offset:9232
	ds_write_b128 v0, v[146:149] offset:18432
	ds_write_b128 v0, v[142:145] offset:18448
	s_and_saveexec_b64 s[12:13], vcc
	s_xor_b64 s[12:13], exec, s[12:13]
	s_or_saveexec_b64 s[12:13], s[12:13]
	s_xor_b64 exec, exec, s[12:13]
	s_cbranch_execz .LBB0_97
	v_lshl_add_u32 v4, v20, 2, 0
	ds_write_b32 v4, v160 offset:44288
	s_branch .LBB0_97
